# skinny GEMM K-loops: 24 loads per batch issued up front instead of load-wait-mfma per step
# speedup vs baseline: 1.0429x; 1.0037x over previous
; #define LAS __attribute__((address_space(3)))
; __device__ __forceinline__ unsigned f2bf(float f) { return pk2(f, 0.f) & 0xffffu; }
; #define p (*kparams())
; __device__ __forceinline__ void skinny_acc(const bf16_t* A, int lda, const bf16_t* Wrow, int ldw, int k_begin, int nk, int r, int h, f32x4 (&acc)[2]) {
;     const bf16_t* a0 = A + (size_t)(MX + 112 + r) * lda + 8 * h + k_begin;
;     const bf16_t* a1 = A + (size_t)(MX + 128 + 112 + r) * lda + 8 * h + k_begin;
;     const bf16_t* bp = Wrow + (size_t)r * ldw + 8 * h + k_begin;
; #pragma unroll 8
;     for (int ks = 0; ks < nk; ++ks) { const bf16x8 x0 = *(const bf16x8*)(a0 + 32 * ks), x1 = *(const bf16x8*)(a1 + 32 * ks), bb = *(const bf16x8*)(bp + 32 * ks);
;         acc[0] = __builtin_amdgcn_mfma_f32_16x16x32_bf16(x0, bb, acc[0], 0, 0, 0); acc[1] = __builtin_amdgcn_mfma_f32_16x16x32_bf16(x1, bb, acc[1], 0, 0, 0); }
; }
; __device__ __forceinline__ void sk_put(LAS float* part, int wave, int lane, const f32x4 (&acc)[2]) {
; #pragma unroll
;     for (int mt = 0; mt < 2; ++mt)
; #pragma unroll
;         for (int q = 0; q < 4; ++q) part[wave * 512 + (mt * 4 + q) * 64 + lane] = acc[mt][q];
; }
; #pragma unroll
;     for (int w8 = 0; w8 < 8; ++w8) s += part[w8 * 512 + tid];
;     return s; }
; __device__ __forceinline__ void skinny_in(CParams& p, int mode, LAS unsigned char* lds) {
;     SK_HEAD
;     const bf16_t* NB = (const bf16_t*)(p.ws + OFF_NB); const bf16_t* WIN = (const bf16_t*)(p.ws + OFF_WIN);
;     const int ntile = mode ? NGATE / 16 : NMIX / 16;
;     for (int tile = blockIdx.x; tile < ntile; tile += gridDim.x) { f32x4 acc[2] = {(f32x4){0.f, 0.f, 0.f, 0.f}, (f32x4){0.f, 0.f, 0.f, 0.f}};
;         __syncthreads();
;         skinny_acc(NB, D, WIN + (size_t)((mode ? NMIX : 0) + tile * 16) * D, D, wave * (D / 8), D / 256, r, h, acc);
;         sk_put(part, wave, lane, acc);
;         __syncthreads();
;         const float sres = sk_sum8(part, tid);
;         if (mode) ((bf16_t*)(p.ws + R_G))[e_row * NGATE + tile * 16 + e_r] = (bf16_t)f2bf(sres);
;         else ((bf16_t*)(p.ws + R_PMIX))[e_row * NMIX + tile * 16 + e_r] = (bf16_t)f2bf(sres); }
.LBB0_223:
	s_ashr_i32 s5, s4, 31
	s_lshl_b64 s[10:11], s[4:5], 12
	s_waitcnt vmcnt(0)
	s_barrier
	v_lshl_add_u64 v[32:33], v[6:7], 0, s[10:11]
	global_load_dwordx4 v[36:39], v[0:1], off
	global_load_dwordx4 v[40:43], v[4:5], off
	global_load_dwordx4 v[44:47], v[32:33], off
	global_load_dwordx4 v[48:51], v[0:1], off offset:64
	global_load_dwordx4 v[52:55], v[4:5], off offset:64
	global_load_dwordx4 v[56:59], v[32:33], off offset:64
	global_load_dwordx4 v[60:63], v[0:1], off offset:128
	global_load_dwordx4 v[64:67], v[4:5], off offset:128
	global_load_dwordx4 v[68:71], v[32:33], off offset:128
	global_load_dwordx4 v[72:75], v[0:1], off offset:192
	global_load_dwordx4 v[76:79], v[4:5], off offset:192
	global_load_dwordx4 v[80:83], v[32:33], off offset:192
	global_load_dwordx4 v[84:87], v[0:1], off offset:256
	global_load_dwordx4 v[88:91], v[4:5], off offset:256
	global_load_dwordx4 v[92:95], v[32:33], off offset:256
	global_load_dwordx4 v[96:99], v[0:1], off offset:320
	global_load_dwordx4 v[100:103], v[4:5], off offset:320
	global_load_dwordx4 v[104:107], v[32:33], off offset:320
	global_load_dwordx4 v[108:111], v[0:1], off offset:384
	global_load_dwordx4 v[112:115], v[4:5], off offset:384
	global_load_dwordx4 v[116:119], v[32:33], off offset:384
	global_load_dwordx4 v[120:123], v[0:1], off offset:448
	global_load_dwordx4 v[124:127], v[4:5], off offset:448
	global_load_dwordx4 v[128:131], v[32:33], off offset:448
	s_waitcnt vmcnt(0)
	s_add_i32 s9, s9, s86
	v_mfma_f32_16x16x32_bf16 v[12:15], v[36:39], v[44:47], 0
	v_mfma_f32_16x16x32_bf16 v[16:19], v[40:43], v[44:47], 0
	v_mfma_f32_16x16x32_bf16 v[12:15], v[48:51], v[56:59], v[12:15]
	v_mfma_f32_16x16x32_bf16 v[16:19], v[52:55], v[56:59], v[16:19]
	v_mfma_f32_16x16x32_bf16 v[12:15], v[60:63], v[68:71], v[12:15]
	v_mfma_f32_16x16x32_bf16 v[16:19], v[64:67], v[68:71], v[16:19]
	v_mfma_f32_16x16x32_bf16 v[12:15], v[72:75], v[80:83], v[12:15]
	v_mfma_f32_16x16x32_bf16 v[16:19], v[76:79], v[80:83], v[16:19]
	v_mfma_f32_16x16x32_bf16 v[12:15], v[84:87], v[92:95], v[12:15]
	v_mfma_f32_16x16x32_bf16 v[16:19], v[88:91], v[92:95], v[16:19]
	v_mfma_f32_16x16x32_bf16 v[12:15], v[96:99], v[104:107], v[12:15]
	v_mfma_f32_16x16x32_bf16 v[16:19], v[100:103], v[104:107], v[16:19]
	v_mfma_f32_16x16x32_bf16 v[12:15], v[108:111], v[116:119], v[12:15]
	v_mfma_f32_16x16x32_bf16 v[16:19], v[112:115], v[116:119], v[16:19]
	v_mfma_f32_16x16x32_bf16 v[12:15], v[120:123], v[128:131], v[12:15]
	v_mfma_f32_16x16x32_bf16 v[16:19], v[124:127], v[128:131], v[16:19]
	s_nop 6
	v_mov_b32_e32 v20, v120
	v_mov_b32_e32 v21, v121
	v_mov_b32_e32 v22, v122
	v_mov_b32_e32 v23, v123
	v_mov_b32_e32 v24, v124
	v_mov_b32_e32 v25, v125
	v_mov_b32_e32 v26, v126
	v_mov_b32_e32 v27, v127
	v_mov_b32_e32 v28, v128
	v_mov_b32_e32 v29, v129
	v_mov_b32_e32 v30, v130
	v_mov_b32_e32 v31, v131
	ds_write2st64_b32 v10, v12, v13 offset1:1
	ds_write2st64_b32 v10, v14, v15 offset0:2 offset1:3
	ds_write2st64_b32 v10, v16, v17 offset0:4 offset1:5
	ds_write2st64_b32 v10, v18, v19 offset0:6 offset1:7
	s_waitcnt lgkmcnt(0)
	s_barrier
	ds_read2st64_b32 v[12:13], v3 offset1:8
	s_waitcnt lgkmcnt(0)
	v_add_f32_e32 v11, 0, v12
	v_add_f32_e32 v11, v11, v13
	ds_read2st64_b32 v[12:13], v3 offset0:16 offset1:24
	s_waitcnt lgkmcnt(0)
	v_add_f32_e32 v11, v11, v12
	v_add_f32_e32 v11, v11, v13
	ds_read2st64_b32 v[12:13], v3 offset0:32 offset1:40
	s_waitcnt lgkmcnt(0)
	v_add_f32_e32 v11, v11, v12
	v_add_f32_e32 v11, v11, v13
	ds_read2st64_b32 v[12:13], v3 offset0:48 offset1:56
	s_waitcnt lgkmcnt(0)
	v_add_f32_e32 v11, v11, v12
	v_add_f32_e32 v11, v11, v13
	v_lshl_add_u64 v[12:13], s[4:5], 1, v[8:9]
	s_add_i32 s4, s4, s14
	v_cvt_pk_bf16_f32 v11, v11, s0
	s_cmpk_lt_i32 s9, 0x1c0
	global_store_short v[12:13], v11, off
	s_cbranch_scc1 .LBB0_223
	s_branch .LBB0_220

; #define LAS __attribute__((address_space(3)))
; __device__ __forceinline__ unsigned f2bf(float f) { return pk2(f, 0.f) & 0xffffu; }
; #define p (*kparams())
; __device__ __forceinline__ void skinny_acc(const bf16_t* A, int lda, const bf16_t* Wrow, int ldw, int k_begin, int nk, int r, int h, f32x4 (&acc)[2]) {
;     const bf16_t* a0 = A + (size_t)(MX + 112 + r) * lda + 8 * h + k_begin;
;     const bf16_t* a1 = A + (size_t)(MX + 128 + 112 + r) * lda + 8 * h + k_begin;
;     const bf16_t* bp = Wrow + (size_t)r * ldw + 8 * h + k_begin;
; #pragma unroll 8
;     for (int ks = 0; ks < nk; ++ks) { const bf16x8 x0 = *(const bf16x8*)(a0 + 32 * ks), x1 = *(const bf16x8*)(a1 + 32 * ks), bb = *(const bf16x8*)(bp + 32 * ks);
;         acc[0] = __builtin_amdgcn_mfma_f32_16x16x32_bf16(x0, bb, acc[0], 0, 0, 0); acc[1] = __builtin_amdgcn_mfma_f32_16x16x32_bf16(x1, bb, acc[1], 0, 0, 0); }
; }
; __device__ __forceinline__ void sk_put(LAS float* part, int wave, int lane, const f32x4 (&acc)[2]) {
; #pragma unroll
;     for (int mt = 0; mt < 2; ++mt)
; #pragma unroll
;         for (int q = 0; q < 4; ++q) part[wave * 512 + (mt * 4 + q) * 64 + lane] = acc[mt][q];
; }
; #pragma unroll
;     for (int w8 = 0; w8 < 8; ++w8) s += part[w8 * 512 + tid];
;     return s; }
; __device__ __forceinline__ void skinny_in(CParams& p, int mode, LAS unsigned char* lds) {
;     SK_HEAD
;     const bf16_t* NB = (const bf16_t*)(p.ws + OFF_NB); const bf16_t* WIN = (const bf16_t*)(p.ws + OFF_WIN);
;     const int ntile = mode ? NGATE / 16 : NMIX / 16;
;     for (int tile = blockIdx.x; tile < ntile; tile += gridDim.x) { f32x4 acc[2] = {(f32x4){0.f, 0.f, 0.f, 0.f}, (f32x4){0.f, 0.f, 0.f, 0.f}};
;         __syncthreads();
;         skinny_acc(NB, D, WIN + (size_t)((mode ? NMIX : 0) + tile * 16) * D, D, wave * (D / 8), D / 256, r, h, acc);
;         sk_put(part, wave, lane, acc);
;         __syncthreads();
;         const float sres = sk_sum8(part, tid);
;         if (mode) ((bf16_t*)(p.ws + R_G))[e_row * NGATE + tile * 16 + e_r] = (bf16_t)f2bf(sres);
;         else ((bf16_t*)(p.ws + R_PMIX))[e_row * NMIX + tile * 16 + e_r] = (bf16_t)f2bf(sres); }
.LBB0_1004:
	s_add_i32 s10, s4, 0x1c00
	s_ashr_i32 s11, s10, 31
	s_lshl_b64 s[10:11], s[10:11], 12
	s_waitcnt vmcnt(0)
	s_barrier
	v_lshl_add_u64 v[32:33], v[6:7], 0, s[10:11]
	global_load_dwordx4 v[36:39], v[0:1], off
	global_load_dwordx4 v[40:43], v[4:5], off
	global_load_dwordx4 v[44:47], v[32:33], off
	global_load_dwordx4 v[48:51], v[0:1], off offset:64
	global_load_dwordx4 v[52:55], v[4:5], off offset:64
	global_load_dwordx4 v[56:59], v[32:33], off offset:64
	global_load_dwordx4 v[60:63], v[0:1], off offset:128
	global_load_dwordx4 v[64:67], v[4:5], off offset:128
	global_load_dwordx4 v[68:71], v[32:33], off offset:128
	global_load_dwordx4 v[72:75], v[0:1], off offset:192
	global_load_dwordx4 v[76:79], v[4:5], off offset:192
	global_load_dwordx4 v[80:83], v[32:33], off offset:192
	global_load_dwordx4 v[84:87], v[0:1], off offset:256
	global_load_dwordx4 v[88:91], v[4:5], off offset:256
	global_load_dwordx4 v[92:95], v[32:33], off offset:256
	global_load_dwordx4 v[96:99], v[0:1], off offset:320
	global_load_dwordx4 v[100:103], v[4:5], off offset:320
	global_load_dwordx4 v[104:107], v[32:33], off offset:320
	global_load_dwordx4 v[108:111], v[0:1], off offset:384
	global_load_dwordx4 v[112:115], v[4:5], off offset:384
	global_load_dwordx4 v[116:119], v[32:33], off offset:384
	global_load_dwordx4 v[120:123], v[0:1], off offset:448
	global_load_dwordx4 v[124:127], v[4:5], off offset:448
	global_load_dwordx4 v[128:131], v[32:33], off offset:448
	s_waitcnt vmcnt(0)
	s_ashr_i32 s5, s4, 31
	s_add_i32 s9, s9, s86
	v_mfma_f32_16x16x32_bf16 v[12:15], v[36:39], v[44:47], 0
	v_mfma_f32_16x16x32_bf16 v[16:19], v[40:43], v[44:47], 0
	v_mfma_f32_16x16x32_bf16 v[12:15], v[48:51], v[56:59], v[12:15]
	v_mfma_f32_16x16x32_bf16 v[16:19], v[52:55], v[56:59], v[16:19]
	v_mfma_f32_16x16x32_bf16 v[12:15], v[60:63], v[68:71], v[12:15]
	v_mfma_f32_16x16x32_bf16 v[16:19], v[64:67], v[68:71], v[16:19]
	v_mfma_f32_16x16x32_bf16 v[12:15], v[72:75], v[80:83], v[12:15]
	v_mfma_f32_16x16x32_bf16 v[16:19], v[76:79], v[80:83], v[16:19]
	v_mfma_f32_16x16x32_bf16 v[12:15], v[84:87], v[92:95], v[12:15]
	v_mfma_f32_16x16x32_bf16 v[16:19], v[88:91], v[92:95], v[16:19]
	v_mfma_f32_16x16x32_bf16 v[12:15], v[96:99], v[104:107], v[12:15]
	v_mfma_f32_16x16x32_bf16 v[16:19], v[100:103], v[104:107], v[16:19]
	v_mfma_f32_16x16x32_bf16 v[12:15], v[108:111], v[116:119], v[12:15]
	v_mfma_f32_16x16x32_bf16 v[16:19], v[112:115], v[116:119], v[16:19]
	v_mfma_f32_16x16x32_bf16 v[12:15], v[120:123], v[128:131], v[12:15]
	v_mfma_f32_16x16x32_bf16 v[16:19], v[124:127], v[128:131], v[16:19]
	s_nop 6
	v_mov_b32_e32 v20, v120
	v_mov_b32_e32 v21, v121
	v_mov_b32_e32 v22, v122
	v_mov_b32_e32 v23, v123
	v_mov_b32_e32 v24, v124
	v_mov_b32_e32 v25, v125
	v_mov_b32_e32 v26, v126
	v_mov_b32_e32 v27, v127
	v_mov_b32_e32 v28, v128
	v_mov_b32_e32 v29, v129
	v_mov_b32_e32 v30, v130
	v_mov_b32_e32 v31, v131
	ds_write2st64_b32 v10, v12, v13 offset1:1
	ds_write2st64_b32 v10, v14, v15 offset0:2 offset1:3
	ds_write2st64_b32 v10, v16, v17 offset0:4 offset1:5
	ds_write2st64_b32 v10, v18, v19 offset0:6 offset1:7
	s_waitcnt lgkmcnt(0)
	s_barrier
	ds_read2st64_b32 v[12:13], v3 offset1:8
	s_waitcnt lgkmcnt(0)
	v_add_f32_e32 v11, 0, v12
	v_add_f32_e32 v11, v11, v13
	ds_read2st64_b32 v[12:13], v3 offset0:16 offset1:24
	s_waitcnt lgkmcnt(0)
	v_add_f32_e32 v11, v11, v12
	v_add_f32_e32 v11, v11, v13
	ds_read2st64_b32 v[12:13], v3 offset0:32 offset1:40
	s_waitcnt lgkmcnt(0)
	v_add_f32_e32 v11, v11, v12
	v_add_f32_e32 v11, v11, v13
	ds_read2st64_b32 v[12:13], v3 offset0:48 offset1:56
	s_waitcnt lgkmcnt(0)
	v_add_f32_e32 v11, v11, v12
	v_add_f32_e32 v11, v11, v13
	v_lshl_add_u64 v[12:13], s[4:5], 1, v[8:9]
	s_add_i32 s4, s4, s14
	v_cvt_pk_bf16_f32 v11, v11, s0
	s_cmpk_lt_i32 s9, 0x200
	global_store_short v[12:13], v11, off
	s_cbranch_scc1 .LBB0_1004
	s_branch .LBB0_1001

; #define LAS __attribute__((address_space(3)))
; __device__ __forceinline__ float bf2f(bf16_t b) { return __uint_as_float(((unsigned)b) << 16); }
; __device__ __forceinline__ unsigned f2bf(float f) { return pk2(f, 0.f) & 0xffffu; }
; __device__ __forceinline__ float sigm(float x) { return __builtin_amdgcn_rcpf(1.0f + __expf(-x)); }
; #define p (*kparams())
; __device__ __forceinline__ void skinny_acc(const bf16_t* A, int lda, const bf16_t* Wrow, int ldw, int k_begin, int nk, int r, int h, f32x4 (&acc)[2]) {
;     const bf16_t* a0 = A + (size_t)(MX + 112 + r) * lda + 8 * h + k_begin;
;     const bf16_t* a1 = A + (size_t)(MX + 128 + 112 + r) * lda + 8 * h + k_begin;
;     const bf16_t* bp = Wrow + (size_t)r * ldw + 8 * h + k_begin;
; #pragma unroll 8
;     for (int ks = 0; ks < nk; ++ks) { const bf16x8 x0 = *(const bf16x8*)(a0 + 32 * ks), x1 = *(const bf16x8*)(a1 + 32 * ks), bb = *(const bf16x8*)(bp + 32 * ks);
;         acc[0] = __builtin_amdgcn_mfma_f32_16x16x32_bf16(x0, bb, acc[0], 0, 0, 0); acc[1] = __builtin_amdgcn_mfma_f32_16x16x32_bf16(x1, bb, acc[1], 0, 0, 0); }
; }
; __device__ __forceinline__ void skinny_branch(CParams& p, LAS unsigned char* lds) {
;     SK_HEAD
;     const bf16_t* Z = (const bf16_t*)(p.ws + OFF_Z); const bf16_t* WBO = (const bf16_t*)(p.ws + OFF_WBO); const bf16_t* G = (const bf16_t*)(p.ws + R_G); bf16_t* MB = (bf16_t*)(p.ws + R_MB);
;     const int z = wave >> 1, kh = wave & 1;
;     for (int tile = blockIdx.x; tile < D / 16; tile += gridDim.x) { f32x4 acc[2] = {(f32x4){0.f, 0.f, 0.f, 0.f}, (f32x4){0.f, 0.f, 0.f, 0.f}};
;         __syncthreads();
;         skinny_acc(Z + z * W, D, WBO + (size_t)z * D * W + (size_t)tile * 16 * W, W, kh * (W / 2), W / 64, r, h, acc);
;         sk_put(part, wave, lane, acc);
;         __syncthreads();
;         float tot = 0.f;
; #pragma unroll
;         for (int zz = 0; zz < 4; ++zz) tot += sigm(bf2f(G[e_row * NGATE + zz * D + tile * 16 + e_r])) * (part[(2 * zz) * 512 + tid] + part[(2 * zz + 1) * 512 + tid]);
;         MB[e_row * D + tile * 16 + e_r] = (bf16_t)f2bf(tot); }
.LBB0_1118:
	s_ashr_i32 s29, s28, 31
	s_lshl_b64 s[10:11], s[28:29], 14
	s_barrier
	v_lshl_add_u64 v[34:35], v[6:7], 0, s[10:11]
	global_load_dwordx4 v[36:39], v[0:1], off
	global_load_dwordx4 v[40:43], v[4:5], off
	global_load_dwordx4 v[44:47], v[34:35], off
	global_load_dwordx4 v[48:51], v[0:1], off offset:64
	global_load_dwordx4 v[52:55], v[4:5], off offset:64
	global_load_dwordx4 v[56:59], v[34:35], off offset:64
	global_load_dwordx4 v[60:63], v[0:1], off offset:128
	global_load_dwordx4 v[64:67], v[4:5], off offset:128
	global_load_dwordx4 v[68:71], v[34:35], off offset:128
	global_load_dwordx4 v[72:75], v[0:1], off offset:192
	global_load_dwordx4 v[76:79], v[4:5], off offset:192
	global_load_dwordx4 v[80:83], v[34:35], off offset:192
	global_load_dwordx4 v[84:87], v[0:1], off offset:256
	global_load_dwordx4 v[88:91], v[4:5], off offset:256
	global_load_dwordx4 v[92:95], v[34:35], off offset:256
	global_load_dwordx4 v[96:99], v[0:1], off offset:320
	global_load_dwordx4 v[100:103], v[4:5], off offset:320
	global_load_dwordx4 v[104:107], v[34:35], off offset:320
	global_load_dwordx4 v[108:111], v[0:1], off offset:384
	global_load_dwordx4 v[112:115], v[4:5], off offset:384
	global_load_dwordx4 v[116:119], v[34:35], off offset:384
	global_load_dwordx4 v[120:123], v[0:1], off offset:448
	global_load_dwordx4 v[124:127], v[4:5], off offset:448
	global_load_dwordx4 v[128:131], v[34:35], off offset:448
	s_waitcnt vmcnt(0)
	s_ashr_i32 s5, s4, 31
	s_lshl_b64 s[14:15], s[4:5], 1
	s_movk_i32 s5, 0x3000
	s_add_i32 s28, s28, s86
	s_add_i32 s4, s4, s9
	s_cmpk_lt_i32 s28, 0x80
	v_mfma_f32_16x16x32_bf16 v[14:17], v[36:39], v[44:47], 0
	v_mfma_f32_16x16x32_bf16 v[18:21], v[40:43], v[44:47], 0
	v_mfma_f32_16x16x32_bf16 v[14:17], v[48:51], v[56:59], v[14:17]
	v_mfma_f32_16x16x32_bf16 v[18:21], v[52:55], v[56:59], v[18:21]
	v_mfma_f32_16x16x32_bf16 v[14:17], v[60:63], v[68:71], v[14:17]
	v_mfma_f32_16x16x32_bf16 v[18:21], v[64:67], v[68:71], v[18:21]
	v_mfma_f32_16x16x32_bf16 v[14:17], v[72:75], v[80:83], v[14:17]
	v_mfma_f32_16x16x32_bf16 v[18:21], v[76:79], v[80:83], v[18:21]
	v_mfma_f32_16x16x32_bf16 v[14:17], v[84:87], v[92:95], v[14:17]
	v_mfma_f32_16x16x32_bf16 v[18:21], v[88:91], v[92:95], v[18:21]
	v_mfma_f32_16x16x32_bf16 v[14:17], v[96:99], v[104:107], v[14:17]
	v_mfma_f32_16x16x32_bf16 v[18:21], v[100:103], v[104:107], v[18:21]
	v_mfma_f32_16x16x32_bf16 v[14:17], v[108:111], v[116:119], v[14:17]
	v_mfma_f32_16x16x32_bf16 v[18:21], v[112:115], v[116:119], v[18:21]
	v_mfma_f32_16x16x32_bf16 v[14:17], v[120:123], v[128:131], v[14:17]
	v_mfma_f32_16x16x32_bf16 v[18:21], v[124:127], v[128:131], v[18:21]
	s_nop 6
	v_mov_b32_e32 v22, v120
	v_mov_b32_e32 v23, v121
	v_mov_b32_e32 v24, v122
	v_mov_b32_e32 v25, v123
	v_mov_b32_e32 v26, v124
	v_mov_b32_e32 v27, v125
	v_mov_b32_e32 v28, v126
	v_mov_b32_e32 v29, v127
	v_mov_b32_e32 v30, v128
	v_mov_b32_e32 v31, v129
	v_mov_b32_e32 v32, v130
	v_mov_b32_e32 v33, v131
	ds_write2st64_b32 v12, v14, v15 offset1:1
	ds_write2st64_b32 v12, v16, v17 offset0:2 offset1:3
	ds_write2st64_b32 v12, v18, v19 offset0:4 offset1:5
	ds_write2st64_b32 v12, v20, v21 offset0:6 offset1:7
	v_lshl_add_u64 v[14:15], v[8:9], 0, s[14:15]
	s_waitcnt lgkmcnt(0)
	s_barrier
	global_load_ushort v13, v[14:15], off
	v_add_co_u32_e32 v20, vcc, s67, v14
	ds_read2st64_b32 v[18:19], v3 offset1:8
	s_nop 0
	v_addc_co_u32_e32 v21, vcc, 0, v15, vcc
	v_add_co_u32_e32 v14, vcc, s5, v14
	ds_read2st64_b32 v[22:23], v3 offset0:16 offset1:24
	s_nop 0
	v_addc_co_u32_e32 v15, vcc, 0, v15, vcc
	s_waitcnt lgkmcnt(1)
	v_mov_b32_e32 v24, v18
	global_load_ushort v14, v[14:15], off
	s_waitcnt lgkmcnt(0)
	v_mov_b32_e32 v25, v22
	v_mov_b32_e32 v22, v19
	v_pk_add_f32 v[18:19], v[24:25], v[22:23]
	s_waitcnt vmcnt(1)
	v_lshlrev_b32_e32 v13, 16, v13
	v_mul_f32_e32 v13, 0xbfb8aa3b, v13
	v_exp_f32_e32 v13, v13
	s_waitcnt vmcnt(0)
	v_lshlrev_b32_e32 v14, 16, v14
	v_add_f32_e32 v13, 1.0, v13
	v_rcp_f32_e32 v16, v13
	global_load_ushort v13, v[20:21], off offset:-4096
	v_mul_f32_e32 v14, 0xbfb8aa3b, v14
	v_exp_f32_e32 v14, v14
	s_waitcnt vmcnt(0)
	v_lshlrev_b32_e32 v13, 16, v13
	v_mul_f32_e32 v13, 0xbfb8aa3b, v13
	v_exp_f32_e32 v13, v13
	v_add_f32_e32 v14, 1.0, v14
	v_add_f32_e32 v13, 1.0, v13
	v_rcp_f32_e32 v17, v13
	s_nop 0
	v_pk_mul_f32 v[16:17], v[18:19], v[16:17]
	s_nop 0
	v_add_f32_e32 v13, 0, v16
	global_load_ushort v16, v[20:21], off
	v_add_f32_e32 v13, v13, v17
	ds_read2st64_b32 v[18:19], v3 offset0:32 offset1:40
	v_rcp_f32_e32 v17, v14
	ds_read2st64_b32 v[14:15], v3 offset0:48 offset1:56
	s_waitcnt lgkmcnt(1)
	v_mov_b32_e32 v20, v18
	s_waitcnt lgkmcnt(0)
	v_mov_b32_e32 v21, v14
	v_mov_b32_e32 v14, v19
	v_pk_add_f32 v[14:15], v[20:21], v[14:15]
	s_waitcnt vmcnt(0)
	v_lshlrev_b32_e32 v16, 16, v16
	v_mul_f32_e32 v16, 0xbfb8aa3b, v16
	v_exp_f32_e32 v16, v16
	s_nop 0
	v_add_f32_e32 v16, 1.0, v16
	v_rcp_f32_e32 v16, v16
	s_nop 0
	v_pk_mul_f32 v[14:15], v[14:15], v[16:17]
	s_nop 0
	v_add_f32_e32 v13, v13, v14
	v_add_f32_e32 v13, v13, v15
	v_cvt_pk_bf16_f32 v13, v13, s0
	v_lshl_add_u64 v[14:15], v[10:11], 0, s[14:15]
	global_store_short v[14:15], v13, off
	s_cbranch_scc1 .LBB0_1118
	s_branch .LBB0_1115

; #define LAS __attribute__((address_space(3)))
; #define p (*kparams())
; __device__ __forceinline__ void skinny_acc(const bf16_t* A, int lda, const bf16_t* Wrow, int ldw, int k_begin, int nk, int r, int h, f32x4 (&acc)[2]) {
;     const bf16_t* a0 = A + (size_t)(MX + 112 + r) * lda + 8 * h + k_begin;
;     const bf16_t* a1 = A + (size_t)(MX + 128 + 112 + r) * lda + 8 * h + k_begin;
;     const bf16_t* bp = Wrow + (size_t)r * ldw + 8 * h + k_begin;
; #pragma unroll 8
;     for (int ks = 0; ks < nk; ++ks) { const bf16x8 x0 = *(const bf16x8*)(a0 + 32 * ks), x1 = *(const bf16x8*)(a1 + 32 * ks), bb = *(const bf16x8*)(bp + 32 * ks);
;         acc[0] = __builtin_amdgcn_mfma_f32_16x16x32_bf16(x0, bb, acc[0], 0, 0, 0); acc[1] = __builtin_amdgcn_mfma_f32_16x16x32_bf16(x1, bb, acc[1], 0, 0, 0); }
; }
; __device__ __forceinline__ void skinny_resid(CParams& p, const bf16_t* A, int lda, const bf16_t* Wt, int K, LAS unsigned char* lds) {
;     SK_HEAD
;     float* H = (float*)(p.ws + OFF_H);
;     for (int tile = blockIdx.x; tile < D / 16; tile += gridDim.x) { f32x4 acc[2] = {(f32x4){0.f, 0.f, 0.f, 0.f}, (f32x4){0.f, 0.f, 0.f, 0.f}};
;         __syncthreads();
;         skinny_acc(A, lda, Wt + (size_t)tile * 16 * K, K, wave * (K / 8), K / 256, r, h, acc);
;         sk_put(part, wave, lane, acc);
;         __syncthreads();
;         H[e_row * D + tile * 16 + e_r] += sk_sum8(part, tid); }
; }
.LBB0_1198:
	s_ashr_i32 s29, s28, 31
	s_lshl_b64 s[10:11], s[28:29], 16
	s_barrier
	v_lshl_add_u64 v[32:33], v[6:7], 0, s[10:11]
	global_load_dwordx4 v[36:39], v[0:1], off
	global_load_dwordx4 v[40:43], v[4:5], off
	global_load_dwordx4 v[44:47], v[32:33], off
	global_load_dwordx4 v[48:51], v[0:1], off offset:64
	global_load_dwordx4 v[52:55], v[4:5], off offset:64
	global_load_dwordx4 v[56:59], v[32:33], off offset:64
	global_load_dwordx4 v[60:63], v[0:1], off offset:128
	global_load_dwordx4 v[64:67], v[4:5], off offset:128
	global_load_dwordx4 v[68:71], v[32:33], off offset:128
	global_load_dwordx4 v[72:75], v[0:1], off offset:192
	global_load_dwordx4 v[76:79], v[4:5], off offset:192
	global_load_dwordx4 v[80:83], v[32:33], off offset:192
	global_load_dwordx4 v[84:87], v[0:1], off offset:256
	global_load_dwordx4 v[88:91], v[4:5], off offset:256
	global_load_dwordx4 v[92:95], v[32:33], off offset:256
	global_load_dwordx4 v[96:99], v[0:1], off offset:320
	global_load_dwordx4 v[100:103], v[4:5], off offset:320
	global_load_dwordx4 v[104:107], v[32:33], off offset:320
	global_load_dwordx4 v[108:111], v[0:1], off offset:384
	global_load_dwordx4 v[112:115], v[4:5], off offset:384
	global_load_dwordx4 v[116:119], v[32:33], off offset:384
	global_load_dwordx4 v[120:123], v[0:1], off offset:448
	global_load_dwordx4 v[124:127], v[4:5], off offset:448
	global_load_dwordx4 v[128:131], v[32:33], off offset:448
	s_waitcnt vmcnt(0)
	s_ashr_i32 s5, s4, 31
	s_add_i32 s28, s28, s86
	v_mfma_f32_16x16x32_bf16 v[12:15], v[36:39], v[44:47], 0
	v_mfma_f32_16x16x32_bf16 v[16:19], v[40:43], v[44:47], 0
	v_mfma_f32_16x16x32_bf16 v[12:15], v[48:51], v[56:59], v[12:15]
	v_mfma_f32_16x16x32_bf16 v[16:19], v[52:55], v[56:59], v[16:19]
	v_mfma_f32_16x16x32_bf16 v[12:15], v[60:63], v[68:71], v[12:15]
	v_mfma_f32_16x16x32_bf16 v[16:19], v[64:67], v[68:71], v[16:19]
	v_mfma_f32_16x16x32_bf16 v[12:15], v[72:75], v[80:83], v[12:15]
	v_mfma_f32_16x16x32_bf16 v[16:19], v[76:79], v[80:83], v[16:19]
	v_mfma_f32_16x16x32_bf16 v[12:15], v[84:87], v[92:95], v[12:15]
	v_mfma_f32_16x16x32_bf16 v[16:19], v[88:91], v[92:95], v[16:19]
	v_mfma_f32_16x16x32_bf16 v[12:15], v[96:99], v[104:107], v[12:15]
	v_mfma_f32_16x16x32_bf16 v[16:19], v[100:103], v[104:107], v[16:19]
	v_mfma_f32_16x16x32_bf16 v[12:15], v[108:111], v[116:119], v[12:15]
	v_mfma_f32_16x16x32_bf16 v[16:19], v[112:115], v[116:119], v[16:19]
	v_mfma_f32_16x16x32_bf16 v[12:15], v[120:123], v[128:131], v[12:15]
	v_mfma_f32_16x16x32_bf16 v[16:19], v[124:127], v[128:131], v[16:19]
	s_nop 6
	v_mov_b32_e32 v20, v120
	v_mov_b32_e32 v21, v121
	v_mov_b32_e32 v22, v122
	v_mov_b32_e32 v23, v123
	v_mov_b32_e32 v24, v124
	v_mov_b32_e32 v25, v125
	v_mov_b32_e32 v26, v126
	v_mov_b32_e32 v27, v127
	v_mov_b32_e32 v28, v128
	v_mov_b32_e32 v29, v129
	v_mov_b32_e32 v30, v130
	v_mov_b32_e32 v31, v131
	ds_write2st64_b32 v10, v12, v13 offset1:1
	ds_write2st64_b32 v10, v14, v15 offset0:2 offset1:3
	ds_write2st64_b32 v10, v16, v17 offset0:4 offset1:5
	ds_write2st64_b32 v10, v18, v19 offset0:6 offset1:7
	s_waitcnt lgkmcnt(0)
	s_barrier
	ds_read2st64_b32 v[12:13], v3 offset1:8
	s_waitcnt lgkmcnt(0)
	v_add_f32_e32 v11, 0, v12
	v_add_f32_e32 v11, v11, v13
	ds_read2st64_b32 v[12:13], v3 offset0:16 offset1:24
	s_waitcnt lgkmcnt(0)
	v_add_f32_e32 v11, v11, v12
	v_add_f32_e32 v11, v11, v13
	ds_read2st64_b32 v[12:13], v3 offset0:32 offset1:40
	s_waitcnt lgkmcnt(0)
	v_add_f32_e32 v11, v11, v12
	v_add_f32_e32 v11, v11, v13
	ds_read2st64_b32 v[12:13], v3 offset0:48 offset1:56
	s_waitcnt lgkmcnt(0)
	v_add_f32_e32 v11, v11, v12
	v_add_f32_e32 v11, v11, v13
	v_lshl_add_u64 v[12:13], s[4:5], 2, v[8:9]
	global_load_dword v14, v[12:13], off
	s_add_i32 s4, s4, s9
	s_cmpk_lt_i32 s28, 0x80
	s_waitcnt vmcnt(0)
	v_add_f32_e32 v11, v14, v11
	global_store_dword v[12:13], v11, off
	s_cbranch_scc1 .LBB0_1198
	s_branch .LBB0_1195

; #define LAS __attribute__((address_space(3)))
; __device__ __forceinline__ unsigned f2bf(float f) { return pk2(f, 0.f) & 0xffffu; }
; __device__ __forceinline__ float siluf(float x) { return x * sigm(x); }
; #define p (*kparams())
; __device__ __forceinline__ void skinny_acc(const bf16_t* A, int lda, const bf16_t* Wrow, int ldw, int k_begin, int nk, int r, int h, f32x4 (&acc)[2]) {
;     const bf16_t* a0 = A + (size_t)(MX + 112 + r) * lda + 8 * h + k_begin;
;     const bf16_t* a1 = A + (size_t)(MX + 128 + 112 + r) * lda + 8 * h + k_begin;
;     const bf16_t* bp = Wrow + (size_t)r * ldw + 8 * h + k_begin;
; #pragma unroll 8
;     for (int ks = 0; ks < nk; ++ks) { const bf16x8 x0 = *(const bf16x8*)(a0 + 32 * ks), x1 = *(const bf16x8*)(a1 + 32 * ks), bb = *(const bf16x8*)(bp + 32 * ks);
;         acc[0] = __builtin_amdgcn_mfma_f32_16x16x32_bf16(x0, bb, acc[0], 0, 0, 0); acc[1] = __builtin_amdgcn_mfma_f32_16x16x32_bf16(x1, bb, acc[1], 0, 0, 0); }
; }
; __device__ __forceinline__ void skinny_swiglu(CParams& p, LAS unsigned char* lds) {
;     SK_HEAD
;     const bf16_t* NB = (const bf16_t*)(p.ws + OFF_NB); const bf16_t* WGU = (const bf16_t*)(p.ws + OFF_WGU); bf16_t* FF = (bf16_t*)(p.ws + R_FF);
;     for (int tile = blockIdx.x; tile < DFF / 16; tile += gridDim.x) { const int c0 = tile * 16, wr0 = 256 * (c0 >> 7) + (c0 & 127);
;         f32x4 ag[2] = {(f32x4){0.f, 0.f, 0.f, 0.f}, (f32x4){0.f, 0.f, 0.f, 0.f}}, au[2] = {(f32x4){0.f, 0.f, 0.f, 0.f}, (f32x4){0.f, 0.f, 0.f, 0.f}};
;         __syncthreads();
;         skinny_acc(NB, D, WGU + (size_t)wr0 * D, D, wave * (D / 8), D / 256, r, h, ag); skinny_acc(NB, D, WGU + (size_t)(wr0 + 128) * D, D, wave * (D / 8), D / 256, r, h, au);
;         sk_put(part, wave, lane, ag); sk_put(part + 4096, wave, lane, au);
;         __syncthreads();
;         const float g = sk_sum8(part, tid), u = sk_sum8(part + 4096, tid);
;         FF[e_row * DFF + c0 + e_r] = (bf16_t)f2bf(siluf(g) * u); }
; }
.LBB0_1327:
	s_and_b32 s5, s9, 0xffffff00
	s_and_b32 s11, s4, 0x70
	s_or_b32 s14, s5, s11
	s_ashr_i32 s15, s14, 31
	s_or_b32 s28, s14, 0x80
	s_lshl_b64 s[14:15], s[14:15], 12
	s_ashr_i32 s29, s28, 31
	v_lshl_add_u64 v[12:13], v[6:7], 0, s[14:15]
	s_lshl_b64 s[14:15], s[28:29], 12
	v_lshl_add_u64 v[10:11], v[6:7], 0, s[14:15]
	s_waitcnt vmcnt(0)
	s_barrier
	global_load_dwordx4 v[44:47], v[0:1], off
	global_load_dwordx4 v[48:51], v[4:5], off
	global_load_dwordx4 v[52:55], v[12:13], off
	global_load_dwordx4 v[56:59], v[10:11], off
	global_load_dwordx4 v[60:63], v[0:1], off offset:64
	global_load_dwordx4 v[64:67], v[4:5], off offset:64
	global_load_dwordx4 v[68:71], v[12:13], off offset:64
	global_load_dwordx4 v[72:75], v[10:11], off offset:64
	global_load_dwordx4 v[76:79], v[0:1], off offset:128
	global_load_dwordx4 v[80:83], v[4:5], off offset:128
	global_load_dwordx4 v[84:87], v[12:13], off offset:128
	global_load_dwordx4 v[88:91], v[10:11], off offset:128
	global_load_dwordx4 v[92:95], v[0:1], off offset:192
	global_load_dwordx4 v[96:99], v[4:5], off offset:192
	global_load_dwordx4 v[100:103], v[12:13], off offset:192
	global_load_dwordx4 v[104:107], v[10:11], off offset:192
	global_load_dwordx4 v[108:111], v[0:1], off offset:256
	global_load_dwordx4 v[112:115], v[4:5], off offset:256
	global_load_dwordx4 v[116:119], v[12:13], off offset:256
	global_load_dwordx4 v[120:123], v[10:11], off offset:256
	global_load_dwordx4 v[124:127], v[0:1], off offset:320
	global_load_dwordx4 v[128:131], v[4:5], off offset:320
	global_load_dwordx4 v[132:135], v[12:13], off offset:320
	global_load_dwordx4 v[136:139], v[10:11], off offset:320
	s_waitcnt vmcnt(0)
	s_ashr_i32 s5, s4, 31
	s_add_i32 s10, s10, s86
	s_add_i32 s9, s9, s31
	v_mfma_f32_16x16x32_bf16 v[28:31], v[44:47], v[52:55], 0
	v_mfma_f32_16x16x32_bf16 v[24:27], v[48:51], v[52:55], 0
	v_mfma_f32_16x16x32_bf16 v[16:19], v[44:47], v[56:59], 0
	v_mfma_f32_16x16x32_bf16 v[20:23], v[48:51], v[56:59], 0
	v_mfma_f32_16x16x32_bf16 v[28:31], v[60:63], v[68:71], v[28:31]
	v_mfma_f32_16x16x32_bf16 v[24:27], v[64:67], v[68:71], v[24:27]
	v_mfma_f32_16x16x32_bf16 v[16:19], v[60:63], v[72:75], v[16:19]
	v_mfma_f32_16x16x32_bf16 v[20:23], v[64:67], v[72:75], v[20:23]
	v_mfma_f32_16x16x32_bf16 v[28:31], v[76:79], v[84:87], v[28:31]
	v_mfma_f32_16x16x32_bf16 v[24:27], v[80:83], v[84:87], v[24:27]
	v_mfma_f32_16x16x32_bf16 v[16:19], v[76:79], v[88:91], v[16:19]
	v_mfma_f32_16x16x32_bf16 v[20:23], v[80:83], v[88:91], v[20:23]
	v_mfma_f32_16x16x32_bf16 v[28:31], v[92:95], v[100:103], v[28:31]
	v_mfma_f32_16x16x32_bf16 v[24:27], v[96:99], v[100:103], v[24:27]
	v_mfma_f32_16x16x32_bf16 v[16:19], v[92:95], v[104:107], v[16:19]
	v_mfma_f32_16x16x32_bf16 v[20:23], v[96:99], v[104:107], v[20:23]
	v_mfma_f32_16x16x32_bf16 v[28:31], v[108:111], v[116:119], v[28:31]
	v_mfma_f32_16x16x32_bf16 v[24:27], v[112:115], v[116:119], v[24:27]
	v_mfma_f32_16x16x32_bf16 v[16:19], v[108:111], v[120:123], v[16:19]
	v_mfma_f32_16x16x32_bf16 v[20:23], v[112:115], v[120:123], v[20:23]
	v_mfma_f32_16x16x32_bf16 v[28:31], v[124:127], v[132:135], v[28:31]
	v_mfma_f32_16x16x32_bf16 v[24:27], v[128:131], v[132:135], v[24:27]
	v_mfma_f32_16x16x32_bf16 v[16:19], v[124:127], v[136:139], v[16:19]
	v_mov_b32_e32 v36, v124
	v_mov_b32_e32 v37, v125
	v_mov_b32_e32 v38, v126
	v_mov_b32_e32 v39, v127
	v_mov_b32_e32 v40, v128
	v_mov_b32_e32 v41, v129
	v_mov_b32_e32 v42, v130
	v_mov_b32_e32 v43, v131
	v_mov_b32_e32 v32, v136
	v_mov_b32_e32 v33, v137
	v_mov_b32_e32 v34, v138
	v_mov_b32_e32 v35, v139
	global_load_dwordx4 v[44:47], v[0:1], off offset:384
	global_load_dwordx4 v[48:51], v[4:5], off offset:384
	global_load_dwordx4 v[52:55], v[12:13], off offset:384
	global_load_dwordx4 v[56:59], v[10:11], off offset:384
	global_load_dwordx4 v[60:63], v[0:1], off offset:448
	global_load_dwordx4 v[64:67], v[4:5], off offset:448
	global_load_dwordx4 v[68:71], v[12:13], off offset:448
	s_nop 0
	global_load_dwordx4 v[72:75], v[10:11], off offset:448
	s_waitcnt vmcnt(0)
	v_mfma_f32_16x16x32_bf16 v[20:23], v[40:43], v[32:35], v[20:23]
	v_mfma_f32_16x16x32_bf16 v[28:31], v[44:47], v[52:55], v[28:31]
	v_mfma_f32_16x16x32_bf16 v[24:27], v[48:51], v[52:55], v[24:27]
	v_mfma_f32_16x16x32_bf16 v[16:19], v[44:47], v[56:59], v[16:19]
	v_mfma_f32_16x16x32_bf16 v[20:23], v[48:51], v[56:59], v[20:23]
	v_mfma_f32_16x16x32_bf16 v[28:31], v[60:63], v[68:71], v[28:31]
	v_mfma_f32_16x16x32_bf16 v[24:27], v[64:67], v[68:71], v[24:27]
	v_mfma_f32_16x16x32_bf16 v[16:19], v[60:63], v[72:75], v[16:19]
	v_mfma_f32_16x16x32_bf16 v[10:13], v[64:67], v[72:75], v[20:23]
	s_nop 3
	v_mov_b32_e32 v36, v60
	v_mov_b32_e32 v37, v61
	v_mov_b32_e32 v38, v62
	v_mov_b32_e32 v39, v63
	v_mov_b32_e32 v40, v64
	v_mov_b32_e32 v41, v65
	v_mov_b32_e32 v42, v66
	v_mov_b32_e32 v43, v67
	v_mov_b32_e32 v32, v68
	v_mov_b32_e32 v33, v69
	v_mov_b32_e32 v34, v70
	v_mov_b32_e32 v35, v71
	ds_write2st64_b32 v14, v28, v29 offset1:1
	ds_write2st64_b32 v14, v30, v31 offset0:2 offset1:3
	ds_write2st64_b32 v14, v24, v25 offset0:4 offset1:5
	ds_write2st64_b32 v14, v26, v27 offset0:6 offset1:7
	ds_write2st64_b32 v14, v16, v17 offset0:64 offset1:65
	ds_write2st64_b32 v14, v18, v19 offset0:66 offset1:67
	ds_write2st64_b32 v14, v10, v11 offset0:68 offset1:69
	ds_write2st64_b32 v14, v12, v13 offset0:70 offset1:71
	s_waitcnt lgkmcnt(0)
	s_barrier
	ds_read2st64_b32 v[10:11], v3 offset1:8
	ds_read2st64_b32 v[12:13], v3 offset0:16 offset1:24
	ds_read2st64_b32 v[16:17], v3 offset0:32 offset1:40
	ds_read2st64_b32 v[18:19], v3 offset0:48 offset1:56
	ds_read2st64_b32 v[20:21], v3 offset0:64 offset1:72
	ds_read2st64_b32 v[22:23], v3 offset0:80 offset1:88
	ds_read2st64_b32 v[24:25], v3 offset0:96 offset1:104
	ds_read2st64_b32 v[26:27], v3 offset0:112 offset1:120
	s_waitcnt lgkmcnt(7)
	v_mov_b32_e32 v28, v10
	s_waitcnt lgkmcnt(3)
	v_mov_b32_e32 v29, v20
	v_mov_b32_e32 v20, v11
	v_mov_b32_e32 v10, v12
	s_waitcnt lgkmcnt(2)
	v_mov_b32_e32 v11, v22
	v_mov_b32_e32 v22, v13
	v_mov_b32_e32 v12, v16
	s_waitcnt lgkmcnt(1)
	v_mov_b32_e32 v13, v24
	v_mov_b32_e32 v24, v17
	v_mov_b32_e32 v16, v18
	s_waitcnt lgkmcnt(0)
	v_mov_b32_e32 v17, v26
	v_mov_b32_e32 v26, v19
	v_pk_add_f32 v[18:19], v[28:29], 0 op_sel_hi:[1,0]
	s_nop 0
	v_pk_add_f32 v[18:19], v[18:19], v[20:21]
	s_nop 0
	v_pk_add_f32 v[10:11], v[18:19], v[10:11]
	s_nop 0
	v_pk_add_f32 v[10:11], v[10:11], v[22:23]
	s_nop 0
	v_pk_add_f32 v[10:11], v[10:11], v[12:13]
	s_nop 0
	v_pk_add_f32 v[10:11], v[10:11], v[24:25]
	s_nop 0
	v_pk_add_f32 v[10:11], v[10:11], v[16:17]
	s_nop 0
	v_pk_add_f32 v[10:11], v[10:11], v[26:27]
	s_nop 0
	v_mul_f32_e32 v12, 0xbfb8aa3b, v10
	v_exp_f32_e32 v12, v12
	s_nop 0
	v_add_f32_e32 v12, 1.0, v12
	v_rcp_f32_e32 v15, v12
	v_lshl_add_u64 v[12:13], s[4:5], 1, v[8:9]
	s_add_i32 s4, s4, s30
	s_cmpk_lt_i32 s10, 0x160
	v_mul_f32_e32 v10, v10, v15
	v_mul_f32_e32 v10, v10, v11
	v_cvt_pk_bf16_f32 v10, v10, s0
	global_store_short v[12:13], v10, off
	s_cbranch_scc1 .LBB0_1327
	s_branch .LBB0_1324

; #define LAS __attribute__((address_space(3)))
; #define p (*kparams())
; __device__ __forceinline__ void skinny_acc(const bf16_t* A, int lda, const bf16_t* Wrow, int ldw, int k_begin, int nk, int r, int h, f32x4 (&acc)[2]) {
;     const bf16_t* a0 = A + (size_t)(MX + 112 + r) * lda + 8 * h + k_begin;
;     const bf16_t* a1 = A + (size_t)(MX + 128 + 112 + r) * lda + 8 * h + k_begin;
;     const bf16_t* bp = Wrow + (size_t)r * ldw + 8 * h + k_begin;
; #pragma unroll 8
;     for (int ks = 0; ks < nk; ++ks) { const bf16x8 x0 = *(const bf16x8*)(a0 + 32 * ks), x1 = *(const bf16x8*)(a1 + 32 * ks), bb = *(const bf16x8*)(bp + 32 * ks);
;         acc[0] = __builtin_amdgcn_mfma_f32_16x16x32_bf16(x0, bb, acc[0], 0, 0, 0); acc[1] = __builtin_amdgcn_mfma_f32_16x16x32_bf16(x1, bb, acc[1], 0, 0, 0); }
; }
; __device__ __forceinline__ void skinny_resid(CParams& p, const bf16_t* A, int lda, const bf16_t* Wt, int K, LAS unsigned char* lds) {
;     SK_HEAD
;     float* H = (float*)(p.ws + OFF_H);
;     for (int tile = blockIdx.x; tile < D / 16; tile += gridDim.x) { f32x4 acc[2] = {(f32x4){0.f, 0.f, 0.f, 0.f}, (f32x4){0.f, 0.f, 0.f, 0.f}};
;         __syncthreads();
;         skinny_acc(A, lda, Wt + (size_t)tile * 16 * K, K, wave * (K / 8), K / 256, r, h, acc);
;         sk_put(part, wave, lane, acc);
;         __syncthreads();
;         H[e_row * D + tile * 16 + e_r] += sk_sum8(part, tid); }
; }
.LBB0_1407:
	v_mov_b32_e32 v10, 0x2c000
	s_barrier
	v_mad_i64_i32 v[10:11], s[14:15], s8, v10, v[6:7]
	global_load_dwordx4 v[36:39], v[0:1], off
	global_load_dwordx4 v[40:43], v[4:5], off
	global_load_dwordx4 v[44:47], v[10:11], off
	global_load_dwordx4 v[48:51], v[0:1], off offset:64
	global_load_dwordx4 v[52:55], v[4:5], off offset:64
	global_load_dwordx4 v[56:59], v[10:11], off offset:64
	global_load_dwordx4 v[60:63], v[0:1], off offset:128
	global_load_dwordx4 v[64:67], v[4:5], off offset:128
	global_load_dwordx4 v[68:71], v[10:11], off offset:128
	global_load_dwordx4 v[72:75], v[0:1], off offset:192
	global_load_dwordx4 v[76:79], v[4:5], off offset:192
	global_load_dwordx4 v[80:83], v[10:11], off offset:192
	global_load_dwordx4 v[84:87], v[0:1], off offset:256
	global_load_dwordx4 v[88:91], v[4:5], off offset:256
	global_load_dwordx4 v[92:95], v[10:11], off offset:256
	global_load_dwordx4 v[96:99], v[0:1], off offset:320
	global_load_dwordx4 v[100:103], v[4:5], off offset:320
	global_load_dwordx4 v[104:107], v[10:11], off offset:320
	global_load_dwordx4 v[108:111], v[0:1], off offset:384
	global_load_dwordx4 v[112:115], v[4:5], off offset:384
	global_load_dwordx4 v[116:119], v[10:11], off offset:384
	global_load_dwordx4 v[120:123], v[0:1], off offset:448
	global_load_dwordx4 v[124:127], v[4:5], off offset:448
	global_load_dwordx4 v[128:131], v[10:11], off offset:448
	s_waitcnt vmcnt(0)
	s_ashr_i32 s5, s4, 31
	s_add_i32 s8, s8, s86
	v_mfma_f32_16x16x32_bf16 v[14:17], v[36:39], v[44:47], 0
	v_mfma_f32_16x16x32_bf16 v[18:21], v[40:43], v[44:47], 0
	v_mfma_f32_16x16x32_bf16 v[14:17], v[48:51], v[56:59], v[14:17]
	v_mfma_f32_16x16x32_bf16 v[18:21], v[52:55], v[56:59], v[18:21]
	v_mfma_f32_16x16x32_bf16 v[14:17], v[60:63], v[68:71], v[14:17]
	v_mfma_f32_16x16x32_bf16 v[18:21], v[64:67], v[68:71], v[18:21]
	v_mfma_f32_16x16x32_bf16 v[14:17], v[72:75], v[80:83], v[14:17]
	v_mfma_f32_16x16x32_bf16 v[18:21], v[76:79], v[80:83], v[18:21]
	v_mfma_f32_16x16x32_bf16 v[14:17], v[84:87], v[92:95], v[14:17]
	v_mfma_f32_16x16x32_bf16 v[18:21], v[88:91], v[92:95], v[18:21]
	v_mfma_f32_16x16x32_bf16 v[14:17], v[96:99], v[104:107], v[14:17]
	v_mfma_f32_16x16x32_bf16 v[18:21], v[100:103], v[104:107], v[18:21]
	v_mfma_f32_16x16x32_bf16 v[14:17], v[108:111], v[116:119], v[14:17]
	v_mfma_f32_16x16x32_bf16 v[18:21], v[112:115], v[116:119], v[18:21]
	v_mfma_f32_16x16x32_bf16 v[14:17], v[120:123], v[128:131], v[14:17]
	v_mfma_f32_16x16x32_bf16 v[18:21], v[124:127], v[128:131], v[18:21]
	v_mov_b32_e32 v22, v120
	v_mov_b32_e32 v23, v121
	v_mov_b32_e32 v24, v122
	v_mov_b32_e32 v25, v123
	v_mov_b32_e32 v26, v124
	v_mov_b32_e32 v27, v125
	v_mov_b32_e32 v28, v126
	v_mov_b32_e32 v29, v127
	v_mov_b32_e32 v30, v128
	v_mov_b32_e32 v31, v129
	v_mov_b32_e32 v32, v130
	v_mov_b32_e32 v33, v131
	global_load_dwordx4 v[36:39], v[0:1], off offset:512
	global_load_dwordx4 v[40:43], v[4:5], off offset:512
	global_load_dwordx4 v[44:47], v[10:11], off offset:512
	global_load_dwordx4 v[48:51], v[0:1], off offset:576
	global_load_dwordx4 v[52:55], v[4:5], off offset:576
	global_load_dwordx4 v[56:59], v[10:11], off offset:576
	global_load_dwordx4 v[60:63], v[0:1], off offset:640
	global_load_dwordx4 v[64:67], v[4:5], off offset:640
	global_load_dwordx4 v[68:71], v[10:11], off offset:640
	global_load_dwordx4 v[72:75], v[0:1], off offset:704
	global_load_dwordx4 v[76:79], v[4:5], off offset:704
	global_load_dwordx4 v[80:83], v[10:11], off offset:704
	global_load_dwordx4 v[84:87], v[0:1], off offset:768
	global_load_dwordx4 v[88:91], v[4:5], off offset:768
	global_load_dwordx4 v[92:95], v[10:11], off offset:768
	global_load_dwordx4 v[96:99], v[0:1], off offset:832
	global_load_dwordx4 v[100:103], v[4:5], off offset:832
	global_load_dwordx4 v[104:107], v[10:11], off offset:832
	global_load_dwordx4 v[108:111], v[0:1], off offset:896
	global_load_dwordx4 v[112:115], v[4:5], off offset:896
	global_load_dwordx4 v[116:119], v[10:11], off offset:896
	global_load_dwordx4 v[120:123], v[0:1], off offset:960
	global_load_dwordx4 v[124:127], v[4:5], off offset:960
	global_load_dwordx4 v[128:131], v[10:11], off offset:960
	s_waitcnt vmcnt(0)
; #define LAS __attribute__((address_space(3)))
; #define p (*kparams())
; __device__ __forceinline__ void skinny_acc(const bf16_t* A, int lda, const bf16_t* Wrow, int ldw, int k_begin, int nk, int r, int h, f32x4 (&acc)[2]) {
;     const bf16_t* a0 = A + (size_t)(MX + 112 + r) * lda + 8 * h + k_begin;
;     const bf16_t* a1 = A + (size_t)(MX + 128 + 112 + r) * lda + 8 * h + k_begin;
;     const bf16_t* bp = Wrow + (size_t)r * ldw + 8 * h + k_begin;
; #pragma unroll 8
;     for (int ks = 0; ks < nk; ++ks) { const bf16x8 x0 = *(const bf16x8*)(a0 + 32 * ks), x1 = *(const bf16x8*)(a1 + 32 * ks), bb = *(const bf16x8*)(bp + 32 * ks);
;         acc[0] = __builtin_amdgcn_mfma_f32_16x16x32_bf16(x0, bb, acc[0], 0, 0, 0); acc[1] = __builtin_amdgcn_mfma_f32_16x16x32_bf16(x1, bb, acc[1], 0, 0, 0); }
; }
; __device__ __forceinline__ void skinny_resid(CParams& p, const bf16_t* A, int lda, const bf16_t* Wt, int K, LAS unsigned char* lds) {
;     SK_HEAD
;     float* H = (float*)(p.ws + OFF_H);
;     for (int tile = blockIdx.x; tile < D / 16; tile += gridDim.x) { f32x4 acc[2] = {(f32x4){0.f, 0.f, 0.f, 0.f}, (f32x4){0.f, 0.f, 0.f, 0.f}};
;         __syncthreads();
;         skinny_acc(A, lda, Wt + (size_t)tile * 16 * K, K, wave * (K / 8), K / 256, r, h, acc);
;         sk_put(part, wave, lane, acc);
;         __syncthreads();
;         H[e_row * D + tile * 16 + e_r] += sk_sum8(part, tid); }
; }
	v_mfma_f32_16x16x32_bf16 v[14:17], v[36:39], v[44:47], v[14:17]
	v_mfma_f32_16x16x32_bf16 v[18:21], v[40:43], v[44:47], v[18:21]
	v_mfma_f32_16x16x32_bf16 v[14:17], v[48:51], v[56:59], v[14:17]
	v_mfma_f32_16x16x32_bf16 v[18:21], v[52:55], v[56:59], v[18:21]
	v_mfma_f32_16x16x32_bf16 v[14:17], v[60:63], v[68:71], v[14:17]
	v_mfma_f32_16x16x32_bf16 v[18:21], v[64:67], v[68:71], v[18:21]
	v_mfma_f32_16x16x32_bf16 v[14:17], v[72:75], v[80:83], v[14:17]
	v_mfma_f32_16x16x32_bf16 v[18:21], v[76:79], v[80:83], v[18:21]
	v_mfma_f32_16x16x32_bf16 v[14:17], v[84:87], v[92:95], v[14:17]
	v_mfma_f32_16x16x32_bf16 v[18:21], v[88:91], v[92:95], v[18:21]
	v_mfma_f32_16x16x32_bf16 v[14:17], v[96:99], v[104:107], v[14:17]
	v_mfma_f32_16x16x32_bf16 v[18:21], v[100:103], v[104:107], v[18:21]
	v_mfma_f32_16x16x32_bf16 v[14:17], v[108:111], v[116:119], v[14:17]
	v_mfma_f32_16x16x32_bf16 v[18:21], v[112:115], v[116:119], v[18:21]
	v_mfma_f32_16x16x32_bf16 v[14:17], v[120:123], v[128:131], v[14:17]
	v_mfma_f32_16x16x32_bf16 v[18:21], v[124:127], v[128:131], v[18:21]
	v_mov_b32_e32 v22, v120
	v_mov_b32_e32 v23, v121
	v_mov_b32_e32 v24, v122
	v_mov_b32_e32 v25, v123
	v_mov_b32_e32 v26, v124
	v_mov_b32_e32 v27, v125
	v_mov_b32_e32 v28, v126
	v_mov_b32_e32 v29, v127
	v_mov_b32_e32 v30, v128
	v_mov_b32_e32 v31, v129
	v_mov_b32_e32 v32, v130
	v_mov_b32_e32 v33, v131
	global_load_dwordx4 v[36:39], v[0:1], off offset:1024
	global_load_dwordx4 v[40:43], v[4:5], off offset:1024
	global_load_dwordx4 v[44:47], v[10:11], off offset:1024
	global_load_dwordx4 v[48:51], v[0:1], off offset:1088
	global_load_dwordx4 v[52:55], v[4:5], off offset:1088
	global_load_dwordx4 v[56:59], v[10:11], off offset:1088
	global_load_dwordx4 v[60:63], v[0:1], off offset:1152
	global_load_dwordx4 v[64:67], v[4:5], off offset:1152
	global_load_dwordx4 v[68:71], v[10:11], off offset:1152
	global_load_dwordx4 v[72:75], v[0:1], off offset:1216
	global_load_dwordx4 v[76:79], v[4:5], off offset:1216
	global_load_dwordx4 v[80:83], v[10:11], off offset:1216
	global_load_dwordx4 v[84:87], v[0:1], off offset:1280
	global_load_dwordx4 v[88:91], v[4:5], off offset:1280
	global_load_dwordx4 v[92:95], v[10:11], off offset:1280
	global_load_dwordx4 v[96:99], v[0:1], off offset:1344
	global_load_dwordx4 v[100:103], v[4:5], off offset:1344
	global_load_dwordx4 v[104:107], v[10:11], off offset:1344
	s_waitcnt vmcnt(0)
	v_mfma_f32_16x16x32_bf16 v[14:17], v[36:39], v[44:47], v[14:17]
	v_mfma_f32_16x16x32_bf16 v[18:21], v[40:43], v[44:47], v[18:21]
	v_mfma_f32_16x16x32_bf16 v[14:17], v[48:51], v[56:59], v[14:17]
	v_mfma_f32_16x16x32_bf16 v[18:21], v[52:55], v[56:59], v[18:21]
	v_mfma_f32_16x16x32_bf16 v[14:17], v[60:63], v[68:71], v[14:17]
	v_mfma_f32_16x16x32_bf16 v[18:21], v[64:67], v[68:71], v[18:21]
	v_mfma_f32_16x16x32_bf16 v[14:17], v[72:75], v[80:83], v[14:17]
	v_mfma_f32_16x16x32_bf16 v[18:21], v[76:79], v[80:83], v[18:21]
	v_mfma_f32_16x16x32_bf16 v[14:17], v[84:87], v[92:95], v[14:17]
	v_mfma_f32_16x16x32_bf16 v[18:21], v[88:91], v[92:95], v[18:21]
	v_mfma_f32_16x16x32_bf16 v[14:17], v[96:99], v[104:107], v[14:17]
	v_mfma_f32_16x16x32_bf16 v[18:21], v[100:103], v[104:107], v[18:21]
	s_nop 6
	v_mov_b32_e32 v22, v96
	v_mov_b32_e32 v23, v97
	v_mov_b32_e32 v24, v98
	v_mov_b32_e32 v25, v99
	v_mov_b32_e32 v26, v100
	v_mov_b32_e32 v27, v101
	v_mov_b32_e32 v28, v102
	v_mov_b32_e32 v29, v103
	v_mov_b32_e32 v30, v104
	v_mov_b32_e32 v31, v105
	v_mov_b32_e32 v32, v106
	v_mov_b32_e32 v33, v107
	ds_write2st64_b32 v12, v14, v15 offset1:1
	ds_write2st64_b32 v12, v16, v17 offset0:2 offset1:3
	ds_write2st64_b32 v12, v18, v19 offset0:4 offset1:5
	ds_write2st64_b32 v12, v20, v21 offset0:6 offset1:7
	s_waitcnt lgkmcnt(0)
	s_barrier
	ds_read2st64_b32 v[10:11], v3 offset1:8
	s_waitcnt lgkmcnt(0)
	v_add_f32_e32 v10, 0, v10
	v_add_f32_e32 v13, v10, v11
	ds_read2st64_b32 v[10:11], v3 offset0:16 offset1:24
	s_waitcnt lgkmcnt(0)
	v_add_f32_e32 v10, v13, v10
	v_add_f32_e32 v13, v10, v11
	ds_read2st64_b32 v[10:11], v3 offset0:32 offset1:40
	s_waitcnt lgkmcnt(0)
	v_add_f32_e32 v10, v13, v10
	v_add_f32_e32 v13, v10, v11
	ds_read2st64_b32 v[10:11], v3 offset0:48 offset1:56
	s_waitcnt lgkmcnt(0)
	v_add_f32_e32 v10, v13, v10
	v_add_f32_e32 v13, v10, v11
	v_lshl_add_u64 v[10:11], s[4:5], 2, v[8:9]
	global_load_dword v14, v[10:11], off
	s_add_i32 s4, s4, s9
	s_cmpk_lt_i32 s8, 0x80
	s_waitcnt vmcnt(0)
	v_add_f32_e32 v13, v14, v13
	global_store_dword v[10:11], v13, off
	s_cbranch_scc1 .LBB0_1407
	s_branch .LBB0_1404
